# v29
# speedup vs baseline: 1.0053x; 1.0053x over previous
.LBB0_243:
	s_and_b32 s36, s12, 1
	s_mul_i32 s37, s36, 0x5600
	v_or_b32_e32 v164, s37, v112
	v_add_u32_e32 v166, v164, v133
	ds_read_b128 v[208:211], v166
	ds_read_b128 v[212:215], v166 offset:6656
	ds_read_b128 v[216:219], v166 offset:32
	ds_read_b128 v[220:223], v166 offset:6688
	ds_read_b128 v[224:227], v166 offset:64
	ds_read_b128 v[228:231], v166 offset:6720
	ds_read_b128 v[232:235], v166 offset:96
	ds_read_b128 v[236:239], v166 offset:6752
	ds_read_b128 v[240:243], v166 offset:128
	ds_read_b128 v[244:247], v166 offset:6784
	ds_read_b128 v[248:251], v166 offset:160
	ds_read_b128 v[252:255], v166 offset:6816
	v_add_u32_e32 v150, s7, v136
	v_mad_i64_i32 v[158:159], s[40:41], v150, s62, v[120:121]
	v_add_u32_e32 v160, s7, v135
	v_add_u32_e32 v162, s7, v134
	v_mad_i64_i32 v[160:161], s[40:41], v160, s62, v[122:123]
	v_mad_i64_i32 v[162:163], s[40:41], v162, s62, v[124:125]
	global_load_dwordx4 v[104:107], v[126:127], off
	global_load_dwordx4 v[108:111], v[128:129], off
	v_lshl_add_u64 v[126:127], v[126:127], 0, s[34:35]
	v_lshl_add_u64 v[128:129], v[128:129], 0, s[34:35]
	global_load_dwordx4 v[146:149], v[158:159], off
	global_load_dwordx4 v[158:161], v[160:161], off
	global_load_dwordx4 v[150:153], v[162:163], off
	s_waitcnt lgkmcnt(11)
	v_mfma_f32_32x32x16_bf16 v[64:79], v[208:211], v[100:103], v[32:47]
	v_add3_u32 v170, v164, v119, v130
	s_waitcnt lgkmcnt(10)
	v_mfma_f32_32x32x16_bf16 v[48:63], v[212:215], v[100:103], v[32:47]
	s_xor_b32 s36, s36, 1
	s_mulk_i32 s36, 0x5600
	v_add_u32_e32 v186, 0x3000, v170
	v_add_u32_e32 v190, 0x4000, v170
	s_add_i32 s12, s12, 1
	s_add_i32 s7, s7, 64
	s_cmpk_lg_i32 s7, 0x1fc0
	s_waitcnt lgkmcnt(9)
	v_mfma_f32_32x32x16_bf16 v[64:79], v[216:219], v[96:99], v[64:79]
	v_add3_u32 v194, s36, v137, v141
	v_add3_u32 v195, s36, v142, v143
	v_add3_u32 v196, s36, v144, v145
	s_waitcnt lgkmcnt(8)
	v_mfma_f32_32x32x16_bf16 v[48:63], v[220:223], v[96:99], v[48:63]
	s_waitcnt lgkmcnt(7)
	v_mfma_f32_32x32x16_bf16 v[64:79], v[224:227], v[92:95], v[64:79]
	s_waitcnt lgkmcnt(6)
	v_mfma_f32_32x32x16_bf16 v[48:63], v[228:231], v[92:95], v[48:63]
	s_waitcnt lgkmcnt(5)
	v_mfma_f32_32x32x16_bf16 v[64:79], v[232:235], v[88:91], v[64:79]
	s_waitcnt lgkmcnt(4)
	v_mfma_f32_32x32x16_bf16 v[48:63], v[236:239], v[88:91], v[48:63]
	s_waitcnt lgkmcnt(3)
	v_mfma_f32_32x32x16_bf16 v[64:79], v[240:243], v[84:87], v[64:79]
	s_waitcnt lgkmcnt(2)
	v_mfma_f32_32x32x16_bf16 v[48:63], v[244:247], v[84:87], v[48:63]
	v_lshl_add_u32 v154, v131, 1, s36
	v_lshl_add_u32 v155, v132, 1, s36
	v_add3_u32 v197, v154, v118, s67
	v_add3_u32 v198, v155, v118, s67
	ds_read2_b64 v[154:157], v186 offset0:128 offset1:130
	s_waitcnt lgkmcnt(2)
	v_mfma_f32_32x32x16_bf16 v[64:79], v[248:251], v[80:83], v[64:79]
	ds_read2_b64 v[162:165], v186 offset0:132 offset1:134
	ds_read2_b64 v[170:173], v190 offset0:160 offset1:162
	ds_read2_b64 v[174:177], v190 offset0:164 offset1:166
	ds_read2_b64 v[178:181], v186 offset0:136 offset1:138
	ds_read2_b64 v[182:185], v190 offset0:168 offset1:170
	ds_read2_b64 v[186:189], v186 offset0:140 offset1:142
	ds_read2_b64 v[190:193], v190 offset0:172 offset1:174
	s_nop 4
	v_exp_f32_e32 v64, v64
	s_waitcnt lgkmcnt(8)
	v_mfma_f32_32x32x16_bf16 v[48:63], v[252:255], v[80:83], v[48:63]
	v_exp_f32_e32 v65, v65
	v_exp_f32_e32 v66, v66
	v_exp_f32_e32 v67, v67
	v_exp_f32_e32 v68, v68
	v_exp_f32_e32 v69, v69
	v_exp_f32_e32 v70, v70
	v_exp_f32_e32 v71, v71
	s_nop 4
	v_exp_f32_e32 v166, v48
	v_exp_f32_e32 v167, v49
	v_exp_f32_e32 v168, v50
	v_exp_f32_e32 v169, v51
	v_cvt_pk_bf16_f32 v48, v64, v65
	v_cvt_pk_bf16_f32 v49, v66, v67
	v_cvt_pk_bf16_f32 v50, v68, v69
	v_cvt_pk_bf16_f32 v51, v70, v71
	v_exp_f32_e32 v72, v72
	v_exp_f32_e32 v73, v73
	s_waitcnt lgkmcnt(7)
	v_mfma_f32_32x32x16_bf16 v[16:31], v[154:157], v[48:51], v[16:31]
	v_exp_f32_e32 v74, v74
	v_exp_f32_e32 v75, v75
	v_exp_f32_e32 v76, v76
	v_exp_f32_e32 v77, v77
	v_exp_f32_e32 v78, v78
	v_exp_f32_e32 v79, v79
	v_add_f32_e32 v64, v115, v64
	s_waitcnt lgkmcnt(5)
	v_mfma_f32_32x32x16_bf16 v[0:15], v[170:173], v[48:51], v[0:15]
	v_add_f32_e32 v64, v65, v64
	v_add_f32_e32 v64, v66, v64
	v_add_f32_e32 v64, v67, v64
	v_exp_f32_e32 v199, v52
	v_exp_f32_e32 v200, v53
	v_exp_f32_e32 v201, v54
	v_exp_f32_e32 v202, v55
	v_cvt_pk_bf16_f32 v52, v72, v73
	v_cvt_pk_bf16_f32 v53, v74, v75
	v_cvt_pk_bf16_f32 v54, v76, v77
	v_cvt_pk_bf16_f32 v55, v78, v79
	v_add_f32_e32 v64, v68, v64
	v_cvt_pk_bf16_f32 v48, v166, v167
	v_mfma_f32_32x32x16_bf16 v[16:31], v[162:165], v[52:55], v[16:31]
	v_cvt_pk_bf16_f32 v49, v168, v169
	v_cvt_pk_bf16_f32 v50, v199, v200
	v_cvt_pk_bf16_f32 v51, v201, v202
	v_exp_f32_e32 v203, v56
	v_exp_f32_e32 v204, v57
	v_exp_f32_e32 v205, v58
	v_exp_f32_e32 v206, v59
	s_waitcnt lgkmcnt(4)
	v_mfma_f32_32x32x16_bf16 v[0:15], v[174:177], v[52:55], v[0:15]
	s_waitcnt vmcnt(2)
	ds_write_b128 v194, v[146:149]
	s_waitcnt vmcnt(1)
	ds_write_b128 v195, v[158:161]
	s_waitcnt vmcnt(0)
	ds_write_b128 v196, v[150:153]
	ds_write2_b64 v197, v[104:105], v[106:107] offset1:1
	ds_write2_b64 v198, v[108:109], v[110:111] offset1:1
	v_add_f32_e32 v52, v69, v64
	v_add_f32_e32 v52, v70, v52
	v_add_f32_e32 v52, v71, v52
	v_add_f32_e32 v52, v72, v52
	v_add_f32_e32 v52, v73, v52
	v_add_f32_e32 v52, v74, v52
	v_add_f32_e32 v52, v75, v52
	v_add_f32_e32 v52, v76, v52
	v_add_f32_e32 v52, v77, v52
	v_add_f32_e32 v52, v78, v52
	v_add_f32_e32 v52, v79, v52
	s_waitcnt lgkmcnt(8)
	v_mfma_f32_32x32x16_bf16 v[16:31], v[178:181], v[48:51], v[16:31]
	v_add_f32_e32 v52, v166, v52
	v_add_f32_e32 v52, v167, v52
	v_exp_f32_e32 v60, v60
	v_exp_f32_e32 v61, v61
	v_exp_f32_e32 v62, v62
	v_exp_f32_e32 v63, v63
	v_cvt_pk_bf16_f32 v56, v203, v204
	s_waitcnt lgkmcnt(7)
	v_mfma_f32_32x32x16_bf16 v[0:15], v[182:185], v[48:51], v[0:15]
	v_add_f32_e32 v48, v168, v52
	v_add_f32_e32 v48, v169, v48
	v_add_f32_e32 v48, v199, v48
	v_add_f32_e32 v48, v200, v48
	v_add_f32_e32 v48, v201, v48
	v_cvt_pk_bf16_f32 v57, v205, v206
	v_cvt_pk_bf16_f32 v58, v60, v61
	v_cvt_pk_bf16_f32 v59, v62, v63
	v_add_f32_e32 v48, v202, v48
	v_add_f32_e32 v48, v203, v48
	s_waitcnt lgkmcnt(6)
	v_mfma_f32_32x32x16_bf16 v[16:31], v[186:189], v[56:59], v[16:31]
	v_add_f32_e32 v48, v204, v48
	v_add_f32_e32 v48, v205, v48
	v_add_f32_e32 v48, v206, v48
	v_add_f32_e32 v48, v60, v48
	v_add_f32_e32 v48, v61, v48
	v_add_f32_e32 v48, v62, v48
	v_add_f32_e32 v115, v63, v48
	s_waitcnt lgkmcnt(5)
	v_mfma_f32_32x32x16_bf16 v[0:15], v[190:193], v[56:59], v[0:15]
	s_waitcnt lgkmcnt(0)
	s_barrier
	s_cbranch_scc1 .LBB0_243
	v_add_u32_e32 v72, v112, v133
	ds_read_b128 v[64:67], v72 offset:22016
	ds_read_b128 v[68:71], v72 offset:22048
	s_lshl_b32 s12, s6, 7
	s_mov_b64 s[6:7], 0
	s_waitcnt lgkmcnt(1)
	v_mfma_f32_32x32x16_bf16 v[48:63], v[64:67], v[100:103], v[32:47]
	s_waitcnt lgkmcnt(0)
	v_mfma_f32_32x32x16_bf16 v[48:63], v[68:71], v[96:99], v[48:63]
	ds_read_b128 v[64:67], v72 offset:22080
	ds_read_b128 v[68:71], v72 offset:22112
	s_waitcnt lgkmcnt(1)
	v_mfma_f32_32x32x16_bf16 v[48:63], v[64:67], v[92:95], v[48:63]
	s_waitcnt lgkmcnt(0)
	v_mfma_f32_32x32x16_bf16 v[48:63], v[68:71], v[88:91], v[48:63]
	ds_read_b128 v[64:67], v72 offset:22144
	ds_read_b128 v[68:71], v72 offset:22176
	s_waitcnt lgkmcnt(1)
	v_mfma_f32_32x32x16_bf16 v[48:63], v[64:67], v[84:87], v[48:63]
	s_waitcnt lgkmcnt(0)
	v_mfma_f32_32x32x16_bf16 v[48:63], v[68:71], v[80:83], v[48:63]
	ds_read_b128 v[64:67], v72 offset:28672
	ds_read_b128 v[68:71], v72 offset:28704
	s_waitcnt lgkmcnt(1)
	v_mfma_f32_32x32x16_bf16 v[32:47], v[64:67], v[100:103], v[32:47]
	s_nop 7
	v_exp_f32_e32 v76, v48
	v_exp_f32_e32 v77, v49
	v_exp_f32_e32 v78, v50
	v_exp_f32_e32 v79, v51
	s_waitcnt lgkmcnt(0)
	v_mfma_f32_32x32x16_bf16 v[32:47], v[68:71], v[96:99], v[32:47]
	ds_read_b128 v[64:67], v72 offset:28736
	ds_read_b128 v[68:71], v72 offset:28768
	s_waitcnt lgkmcnt(1)
	v_mfma_f32_32x32x16_bf16 v[32:47], v[64:67], v[92:95], v[32:47]
	ds_read_b128 v[64:67], v72 offset:28800
	ds_read_b128 v[72:75], v72 offset:28832
	v_exp_f32_e32 v92, v56
	v_exp_f32_e32 v93, v61
	v_exp_f32_e32 v94, v62
	v_exp_f32_e32 v95, v63
	s_nop 0
	v_cvt_pk_bf16_f32 v51, v94, v95
	s_waitcnt lgkmcnt(2)
	v_mfma_f32_32x32x16_bf16 v[32:47], v[68:71], v[88:91], v[32:47]
	v_exp_f32_e32 v88, v52
	v_exp_f32_e32 v89, v53
	v_exp_f32_e32 v90, v54
	v_exp_f32_e32 v91, v55
	s_waitcnt lgkmcnt(1)
	v_mfma_f32_32x32x16_bf16 v[32:47], v[64:67], v[84:87], v[32:47]
	v_exp_f32_e32 v84, v57
	v_exp_f32_e32 v85, v58
	v_exp_f32_e32 v86, v59
	v_exp_f32_e32 v87, v60
	v_cvt_pk_bf16_f32 v48, v92, v84
	v_cvt_pk_bf16_f32 v49, v85, v86
	s_waitcnt lgkmcnt(0)
	v_mfma_f32_32x32x16_bf16 v[32:47], v[72:75], v[80:83], v[32:47]
	v_cvt_pk_bf16_f32 v50, v87, v93
	s_nop 10
	v_exp_f32_e32 v72, v32
	v_cvt_pk_bf16_f32 v32, v76, v77
	v_add_f32_e32 v76, v115, v76
	v_add_f32_e32 v76, v77, v76
	v_add_f32_e32 v76, v78, v76
	v_add_f32_e32 v76, v79, v76
	v_add_f32_e32 v76, v88, v76
	v_add_f32_e32 v76, v89, v76
	v_add_f32_e32 v76, v90, v76
	v_add_f32_e32 v76, v91, v76
	v_add_f32_e32 v76, v92, v76
	v_add_f32_e32 v76, v84, v76
	v_add_f32_e32 v76, v85, v76
	v_exp_f32_e32 v100, v44
	v_add3_u32 v44, v112, v119, v130
	v_add_f32_e32 v76, v86, v76
	v_exp_f32_e32 v73, v33
	v_add_u32_e32 v104, 0x8800, v44
	v_add_u32_e32 v105, 0x9800, v44
	v_add_f32_e32 v76, v87, v76
	v_exp_f32_e32 v80, v36
	v_exp_f32_e32 v81, v37
	v_exp_f32_e32 v82, v38
	v_exp_f32_e32 v83, v39
	v_exp_f32_e32 v96, v40
	v_exp_f32_e32 v97, v41
	v_exp_f32_e32 v98, v42
	v_exp_f32_e32 v99, v43
	v_exp_f32_e32 v101, v45
	v_exp_f32_e32 v102, v46
	v_exp_f32_e32 v103, v47
	ds_read2_b64 v[36:39], v104 offset0:64 offset1:66
	ds_read2_b64 v[40:43], v104 offset0:68 offset1:70
	ds_read2_b64 v[44:47], v105 offset0:96 offset1:98
	v_add_f32_e32 v76, v93, v76
	v_exp_f32_e32 v74, v34
	v_add_f32_e32 v76, v94, v76
	v_exp_f32_e32 v75, v35
	v_add_f32_e32 v76, v95, v76
	v_cvt_pk_bf16_f32 v56, v72, v73
	v_add_f32_e32 v72, v72, v76
	v_add_f32_e32 v72, v73, v72
	v_add_f32_e32 v72, v74, v72
	v_cvt_pk_bf16_f32 v33, v78, v79
	v_cvt_pk_bf16_f32 v34, v88, v89
	v_cvt_pk_bf16_f32 v35, v90, v91
	v_add_f32_e32 v72, v75, v72
	ds_read2_b64 v[52:55], v105 offset0:100 offset1:102
	s_waitcnt lgkmcnt(3)
	v_mfma_f32_32x32x16_bf16 v[16:31], v[36:39], v[32:35], v[16:31]
	v_add_f32_e32 v36, v80, v72
	v_add_f32_e32 v36, v81, v36
	v_add_f32_e32 v36, v82, v36
	v_add_f32_e32 v36, v83, v36
	v_add_f32_e32 v36, v96, v36
	v_add_f32_e32 v36, v97, v36
	v_add_f32_e32 v36, v98, v36
	s_waitcnt lgkmcnt(1)
	v_mfma_f32_32x32x16_bf16 v[0:15], v[44:47], v[32:35], v[0:15]
	v_add_f32_e32 v32, v99, v36
	v_add_f32_e32 v32, v100, v32
	v_add_f32_e32 v32, v101, v32
	v_add_f32_e32 v32, v102, v32
	v_and_b32_e32 v33, 64, v139
	v_add_f32_e32 v44, v103, v32
	v_xor_b32_e32 v32, 32, v139
	v_mfma_f32_32x32x16_bf16 v[16:31], v[40:43], v[48:51], v[16:31]
	v_add_u32_e32 v33, 64, v33
	v_cmp_lt_i32_e32 vcc, v32, v33
	ds_read2_b64 v[60:63], v104 offset0:72 offset1:74
	ds_read2_b64 v[64:67], v105 offset0:104 offset1:106
	v_cndmask_b32_e32 v32, v139, v32, vcc
	v_lshlrev_b32_e32 v32, 2, v32
	ds_bpermute_b32 v40, v32, v44
	v_cvt_pk_bf16_f32 v57, v74, v75
	s_waitcnt lgkmcnt(3)
	v_mfma_f32_32x32x16_bf16 v[0:15], v[52:55], v[48:51], v[0:15]
	v_cvt_pk_bf16_f32 v58, v80, v81
	v_cvt_pk_bf16_f32 v59, v82, v83
	s_waitcnt lgkmcnt(0)
	v_add_f32_e32 v40, v44, v40
	ds_read2_b64 v[32:35], v104 offset0:76 offset1:78
	ds_read2_b64 v[36:39], v105 offset0:108 offset1:110
	v_div_scale_f32 v41, s[36:37], v40, v40, 1.0
	v_rcp_f32_e32 v42, v41
	v_mfma_f32_32x32x16_bf16 v[16:31], v[60:63], v[56:59], v[16:31]
	v_cvt_pk_bf16_f32 v68, v96, v97
	v_cvt_pk_bf16_f32 v69, v98, v99
	v_cvt_pk_bf16_f32 v70, v100, v101
	v_cvt_pk_bf16_f32 v71, v102, v103
	v_fma_f32 v43, -v41, v42, 1.0
	v_fmac_f32_e32 v42, v43, v42
	v_div_scale_f32 v43, vcc, 1.0, v40, 1.0
	v_mfma_f32_32x32x16_bf16 v[0:15], v[64:67], v[56:59], v[0:15]
	v_mul_f32_e32 v44, v43, v42
	v_fma_f32 v45, -v41, v44, v43
	v_fmac_f32_e32 v44, v45, v42
	v_fma_f32 v41, -v41, v44, v43
	v_div_fmas_f32 v41, v41, v42, v44
	v_lshlrev_b64 v[42:43], 10, v[116:117]
	v_div_fixup_f32 v40, v41, v40, 1.0
	s_waitcnt lgkmcnt(1)
	v_mfma_f32_32x32x16_bf16 v[16:31], v[32:35], v[68:71], v[16:31]
	v_lshl_add_u64 v[42:43], s[8:9], 0, v[42:43]
	v_lshl_add_u64 v[32:33], v[42:43], 0, s[12:13]
	v_mov_b32_e32 v115, v113
	v_lshl_add_u64 v[32:33], v[32:33], 0, v[114:115]
	s_waitcnt lgkmcnt(0)
	s_barrier
	v_mfma_f32_32x32x16_bf16 v[0:15], v[36:39], v[68:71], v[0:15]
	s_nop 4
	v_mul_f32_e64 v16, v16, v40
	v_mul_f32_e64 v17, v17, v40
	v_mul_f32_e64 v18, v18, v40
	v_mul_f32_e64 v19, v19, v40
	v_cvt_pk_bf16_f32 v16, v16, v17
	v_cvt_pk_bf16_f32 v17, v18, v19
	global_store_dwordx2 v[32:33], v[16:17], off
	v_pk_mul_f32 v[16:17], v[20:21], v[40:41] op_sel_hi:[1,0]
	v_pk_mul_f32 v[18:19], v[22:23], v[40:41] op_sel_hi:[1,0]
	v_pk_mul_f32 v[0:1], v[0:1], v[40:41] op_sel_hi:[1,0]
	v_pk_mul_f32 v[2:3], v[2:3], v[40:41] op_sel_hi:[1,0]
	v_cvt_pk_bf16_f32 v0, v0, v1
	v_cvt_pk_bf16_f32 v1, v2, v3
	global_store_dwordx2 v[32:33], v[0:1], off offset:64
	v_pk_mul_f32 v[0:1], v[4:5], v[40:41] op_sel_hi:[1,0]
	v_pk_mul_f32 v[2:3], v[6:7], v[40:41] op_sel_hi:[1,0]
	v_cvt_pk_bf16_f32 v16, v16, v17
	v_cvt_pk_bf16_f32 v17, v18, v19
	v_cvt_pk_bf16_f32 v0, v0, v1
	v_cvt_pk_bf16_f32 v1, v2, v3
	global_store_dwordx2 v[32:33], v[16:17], off offset:16
	v_pk_mul_f32 v[16:17], v[24:25], v[40:41] op_sel_hi:[1,0]
	v_pk_mul_f32 v[18:19], v[26:27], v[40:41] op_sel_hi:[1,0]
	global_store_dwordx2 v[32:33], v[0:1], off offset:80
	v_pk_mul_f32 v[0:1], v[8:9], v[40:41] op_sel_hi:[1,0]
	v_pk_mul_f32 v[2:3], v[10:11], v[40:41] op_sel_hi:[1,0]
	v_cvt_pk_bf16_f32 v16, v16, v17
	v_cvt_pk_bf16_f32 v17, v18, v19
	v_cvt_pk_bf16_f32 v0, v0, v1
	v_cvt_pk_bf16_f32 v1, v2, v3
	global_store_dwordx2 v[32:33], v[16:17], off offset:32
	v_pk_mul_f32 v[16:17], v[28:29], v[40:41] op_sel_hi:[1,0]
	v_pk_mul_f32 v[18:19], v[30:31], v[40:41] op_sel_hi:[1,0]
	global_store_dwordx2 v[32:33], v[0:1], off offset:96
	v_pk_mul_f32 v[0:1], v[12:13], v[40:41] op_sel_hi:[1,0]
	v_pk_mul_f32 v[2:3], v[14:15], v[40:41] op_sel_hi:[1,0]
	v_cvt_pk_bf16_f32 v16, v16, v17
	v_cvt_pk_bf16_f32 v17, v18, v19
	v_cvt_pk_bf16_f32 v0, v0, v1
	v_cvt_pk_bf16_f32 v1, v2, v3
	global_store_dwordx2 v[32:33], v[16:17], off offset:48
	global_store_dwordx2 v[32:33], v[0:1], off offset:112
